# compressed pass 2: removed a redundant 9-state s_nop at the importance join point and four never-taken execz branches
# baseline (speedup 1.0000x reference)
; __device__ __forceinline__ float quad_sum(float x) { x += dpp_f<0xB1>(x); x += dpp_f<0x4E>(x); return x; }
; __device__ __forceinline__ void nsa_unit(const Params& p, int bg, int jq, LAS unsigned char* lds, int wave, int lane, bool build_lut) {
;     ...
; #pragma unroll
;             for (int i4 = 0; i4 < 4; ++i4) {
;                 float a = (s[4 * i4] + s[4 * i4 + 1]) + (s[4 * i4 + 2] + 0.5f * s[4 * i4 + 3]);
;                 float bb = 0.5f * s[4 * i4 + 3];
;                 a = quad_sum(a); bb = quad_sum(bb);
;                 if (r == i4) {
;                     const int n = 8 * T + 2 * i4 + h;
;                     atomicAdd((float*)(imp + ql * 256 + n), a);
;                     if (n + 1 < 256) atomicAdd((float*)(imp + ql * 256 + n + 1), bb);
;                 }
;             }
.LBB0_1133:
	v_add_f32_e32 v34, v50, v51
	v_fma_f32 v36, 0.5, v53, v52
	v_mul_f32_e32 v35, 0.5, v53
	v_add_f32_e32 v34, v34, v36
	s_nop 1
	v_add_f32_dpp v36, v34, v34 quad_perm:[1,0,3,2] row_mask:0xf bank_mask:0xf bound_ctrl:1
	v_mov_b32_dpp v34, v35 quad_perm:[1,0,3,2] row_mask:0xf bank_mask:0xf bound_ctrl:1
	v_fmac_f32_e32 v34, 0.5, v53
	v_mov_b32_dpp v37, v36 quad_perm:[2,3,0,1] row_mask:0xf bank_mask:0xf bound_ctrl:1
	s_nop 0
	v_mov_b32_dpp v35, v34 quad_perm:[2,3,0,1] row_mask:0xf bank_mask:0xf bound_ctrl:1
	s_and_saveexec_b64 s[18:19], s[6:7]
	v_add_f32_e32 v36, v36, v37
	ds_add_f32 v121, v36
	s_movk_i32 s25, 0xff
	v_cmp_gt_i32_e32 vcc, s25, v123
	s_and_b64 exec, exec, vcc
	v_add_f32_e32 v34, v34, v35
	ds_add_f32 v121, v34 offset:4
.LBB0_1136:
	s_or_b64 exec, exec, s[18:19]
	v_add_f32_e32 v34, v54, v55
	v_fma_f32 v36, 0.5, v57, v56
	v_mul_f32_e32 v35, 0.5, v57
	v_add_f32_e32 v34, v34, v36
	s_nop 1
	v_add_f32_dpp v36, v34, v34 quad_perm:[1,0,3,2] row_mask:0xf bank_mask:0xf bound_ctrl:1
	v_mov_b32_dpp v34, v35 quad_perm:[1,0,3,2] row_mask:0xf bank_mask:0xf bound_ctrl:1
	v_fmac_f32_e32 v34, 0.5, v57
	v_mov_b32_dpp v37, v36 quad_perm:[2,3,0,1] row_mask:0xf bank_mask:0xf bound_ctrl:1
	s_nop 0
	v_mov_b32_dpp v35, v34 quad_perm:[2,3,0,1] row_mask:0xf bank_mask:0xf bound_ctrl:1
	s_and_saveexec_b64 s[18:19], s[8:9]
	v_add_f32_e32 v36, v36, v37
	ds_add_f32 v121, v36 offset:8
	s_movk_i32 s25, 0xfd
	v_cmp_gt_i32_e32 vcc, s25, v123
	s_and_b64 exec, exec, vcc
	v_add_f32_e32 v34, v34, v35
	ds_add_f32 v121, v34 offset:12
.LBB0_1139:
	s_or_b64 exec, exec, s[18:19]
	v_add_f32_e32 v34, v58, v59
	v_fma_f32 v36, 0.5, v61, v60
	v_mul_f32_e32 v35, 0.5, v61
	v_add_f32_e32 v34, v34, v36
	s_nop 1
	v_add_f32_dpp v36, v34, v34 quad_perm:[1,0,3,2] row_mask:0xf bank_mask:0xf bound_ctrl:1
	v_mov_b32_dpp v34, v35 quad_perm:[1,0,3,2] row_mask:0xf bank_mask:0xf bound_ctrl:1
	v_fmac_f32_e32 v34, 0.5, v61
	v_mov_b32_dpp v37, v36 quad_perm:[2,3,0,1] row_mask:0xf bank_mask:0xf bound_ctrl:1
	s_nop 0
	v_mov_b32_dpp v35, v34 quad_perm:[2,3,0,1] row_mask:0xf bank_mask:0xf bound_ctrl:1
	s_and_saveexec_b64 s[18:19], s[10:11]
	v_add_f32_e32 v36, v36, v37
	ds_add_f32 v121, v36 offset:16
	s_movk_i32 s25, 0xfb
	v_cmp_gt_i32_e32 vcc, s25, v123
	s_and_b64 exec, exec, vcc
	v_add_f32_e32 v34, v34, v35
	ds_add_f32 v121, v34 offset:20
.LBB0_1142:
	s_or_b64 exec, exec, s[18:19]
	v_exp_f32_e32 v34, v65
	v_add_f32_e32 v35, v62, v63
	v_mul_f32_e32 v36, 0.5, v34
	v_fma_f32 v37, 0.5, v34, v64
	v_add_f32_e32 v37, v35, v37
	v_mov_b32_dpp v35, v36 quad_perm:[1,0,3,2] row_mask:0xf bank_mask:0xf bound_ctrl:1
	v_fmac_f32_e32 v35, 0.5, v34
	v_add_f32_dpp v37, v37, v37 quad_perm:[1,0,3,2] row_mask:0xf bank_mask:0xf bound_ctrl:1
	s_nop 0
	v_mov_b32_dpp v36, v35 quad_perm:[2,3,0,1] row_mask:0xf bank_mask:0xf bound_ctrl:1
	v_mov_b32_dpp v38, v37 quad_perm:[2,3,0,1] row_mask:0xf bank_mask:0xf bound_ctrl:1
	s_and_saveexec_b64 s[18:19], s[12:13]
	v_add_f32_e32 v37, v37, v38
	ds_add_f32 v121, v37 offset:24
	s_movk_i32 s25, 0xf9
	v_cmp_gt_i32_e32 vcc, s25, v123
	s_and_b64 exec, exec, vcc
	v_add_f32_e32 v35, v35, v36
	ds_add_f32 v121, v35 offset:28
